# helper derive in one pass (all raw reads up front, no intermediate LDS drains), compute waves flush both y halves, helper priority 3
# baseline (speedup 1.0000x reference)
.LBB0_670:
	s_cmpk_ge_u32 s62, 0x100
	s_cbranch_scc1 .LBB0_672
	s_cmp_eq_u32 s65, 0
	s_cbranch_scc1 .LBB0_672
	s_and_b32 s22, s64, 0x800
	v_lshl_add_u32 v21, s22, 2, v68
	v_cndmask_b32_e64 v76, v71, v70, s[4:5]
	ds_read_b128 v[72:75], v21
	v_ashrrev_i32_e32 v77, 31, v76
	v_lshl_add_u64 v[76:77], v[76:77], 0, s[40:41]
	v_lshlrev_b64 v[76:77], 12, v[76:77]
	v_lshl_add_u64 v[76:77], v[54:55], 0, v[76:77]
	s_waitcnt lgkmcnt(0)
	global_store_dwordx4 v[76:77], v[72:75], off

.Lmy_f_main:
	s_cmpk_ge_u32 s62, 0x100
	s_cbranch_scc1 .Lmy_f_hlp
	s_cmp_eq_u32 s65, 0
	s_cbranch_scc1 .Lmy_f_nofl
	v_add_u32_e32 v70, 16, v70
	v_subrev_u32_e32 v71, 16, v71
	s_and_b32 s96, s64, 0x800
	v_lshl_add_u32 v21, s96, 2, v68
	v_add_u32_e32 v21, 0x1000, v21
	v_cndmask_b32_e64 v76, v71, v70, s[4:5]
	ds_read_b128 v[72:75], v21
	v_ashrrev_i32_e32 v77, 31, v76
	v_lshl_add_u64 v[76:77], v[76:77], 0, s[40:41]
	v_lshlrev_b64 v[76:77], 12, v[76:77]
	v_lshl_add_u64 v[76:77], v[54:55], 0, v[76:77]
	v_subrev_u32_e32 v70, 16, v70
	v_add_u32_e32 v71, 16, v71
	s_waitcnt lgkmcnt(0)
	global_store_dwordx4 v[76:77], v[72:75], off
.Lmy_f_nofl:
	s_cmp_lg_u32 s65, 0
	s_cbranch_scc1 .Lmy_ck_nz
	v_mov_b32_e32 v208, 0
	v_mov_b32_e32 v209, 0
	v_mov_b32_e32 v210, 0
	v_mov_b32_e32 v211, 0
	v_mov_b32_e32 v212, 0
	v_mov_b32_e32 v213, 0
	v_mov_b32_e32 v214, 0
	v_mov_b32_e32 v215, 0
	v_mov_b32_e32 v216, 0
	v_mov_b32_e32 v217, 0
	v_mov_b32_e32 v218, 0
	v_mov_b32_e32 v219, 0
	v_mov_b32_e32 v220, 0
	v_mov_b32_e32 v221, 0
	v_mov_b32_e32 v222, 0
	v_mov_b32_e32 v223, 0

.Lmy_f_nol34:
	s_bfe_u32 s96, s62, 0x20006
	s_lshl_b32 s100, s96, 11
	v_lshl_add_u32 v72, v224, 2, s100
	s_and_b32 s97, s96, 1
	s_mul_i32 s97, s97, 0x2700
	s_mov_b32 s101, 0x1c000
	s_mov_b32 s100, 0x6100
	s_bitcmp0_b32 s65, 0
	s_cselect_b32 s101, 0xe000, s101
	s_cselect_b32 s100, 0x4e00, s100
	s_cmp_gt_u32 s96, 1
	s_cselect_b32 s100, s100, 0
	s_add_i32 s97, s97, s101
	s_add_i32 s97, s97, s100
	ds_read_b32 v80, v72
	ds_read_b32 v81, v72 offset:256
	ds_read_b32 v82, v72 offset:512
	ds_read_b32 v83, v72 offset:768
	ds_read_b32 v84, v72 offset:1024
	ds_read_b32 v85, v72 offset:1280
	ds_read_b32 v86, v72 offset:1536
	ds_read_b32 v87, v72 offset:1792
	ds_read_b32 v88, v72 offset:8192
	ds_read_b32 v89, v72 offset:8448
	ds_read_b32 v90, v72 offset:8704
	ds_read_b32 v91, v72 offset:8960
	ds_read_b32 v92, v72 offset:9216
	ds_read_b32 v93, v72 offset:9472
	ds_read_b32 v94, v72 offset:9728
	ds_read_b32 v95, v72 offset:9984
	ds_read_b32 v96, v72 offset:32768
	ds_read_b32 v97, v72 offset:33024
	ds_read_b32 v98, v72 offset:33280
	ds_read_b32 v99, v72 offset:33536
	ds_read_b32 v100, v72 offset:33792
	ds_read_b32 v101, v72 offset:34048
	ds_read_b32 v102, v72 offset:34304
	ds_read_b32 v103, v72 offset:34560
	ds_read_b32 v180, v72 offset:16384
	ds_read_b32 v181, v72 offset:16640
	ds_read_b32 v182, v72 offset:16896
	ds_read_b32 v183, v72 offset:17152
	ds_read_b32 v184, v72 offset:17408
	ds_read_b32 v185, v72 offset:17664
	ds_read_b32 v186, v72 offset:17920
	ds_read_b32 v187, v72 offset:18176
	ds_read_b32 v188, v72 offset:24576
	ds_read_b32 v189, v72 offset:24832
	ds_read_b32 v190, v72 offset:25088
	ds_read_b32 v191, v72 offset:25344
	ds_read_b32 v192, v72 offset:25600
	ds_read_b32 v193, v72 offset:25856
	ds_read_b32 v194, v72 offset:26112
	ds_read_b32 v195, v72 offset:26368
	v_and_b32_e32 v74, 3, v224
	v_bfe_u32 v75, v224, 2, 2
	v_lshrrev_b32_e32 v76, 4, v224
	v_lshlrev_b32_e32 v74, 2, v74
	v_lshl_add_u32 v74, v75, 8, v74
	v_lshl_add_u32 v74, v76, 10, v74
	s_add_i32 s100, s97, 0x0
	v_add_u32_e32 v74, s100, v74
	v_and_b32_e32 v196, 15, v224
	v_lshlrev_b32_e32 v196, 4, v196
	v_lshl_add_u32 v196, v76, 10, v196
	s_add_i32 s101, s97, 0x1000
	v_add_u32_e32 v196, s101, v196
	s_add_i32 s101, s97, 0x2000
	v_lshl_add_u32 v197, v224, 2, s101
	v_xor_b32_e32 v76, 0, v75
	v_xor_b32_e32 v77, 1, v75
	v_xor_b32_e32 v78, 2, v75
	v_xor_b32_e32 v79, 3, v75
	v_lshl_add_u32 v76, v76, 4, v74
	v_lshl_add_u32 v77, v77, 4, v74
	v_lshl_add_u32 v78, v78, 4, v74
	v_lshl_add_u32 v79, v79, 4, v74
	s_waitcnt lgkmcnt(15)
	v_mov_b32_e32 v104, v80
	v_mul_f32_e32 v105, v104, v81
	v_mul_f32_e32 v106, v105, v82
	v_mul_f32_e32 v107, v106, v83
	v_mul_f32_e32 v108, v107, v84
	v_mul_f32_e32 v109, v108, v85
	v_mul_f32_e32 v110, v109, v86
	v_mul_f32_e32 v111, v110, v87
	v_rcp_f32_e32 v216, v104
	v_rcp_f32_e32 v217, v105
	v_rcp_f32_e32 v218, v106
	v_rcp_f32_e32 v219, v107
	v_rcp_f32_e32 v220, v108
	v_rcp_f32_e32 v221, v109
	v_rcp_f32_e32 v222, v110
	v_rcp_f32_e32 v223, v111
	v_mov_b32_e32 v112, v88
	v_mul_f32_e32 v113, v104, v89
	v_mul_f32_e32 v114, v105, v90
	v_mul_f32_e32 v115, v106, v91
	v_mul_f32_e32 v116, v107, v92
	v_mul_f32_e32 v117, v108, v93
	v_mul_f32_e32 v118, v109, v94
	v_mul_f32_e32 v119, v110, v95
	v_mul_f32_e32 v120, v104, v96
	v_mul_f32_e32 v121, v105, v97
	v_mul_f32_e32 v122, v106, v98
	v_mul_f32_e32 v123, v107, v99
	v_mul_f32_e32 v124, v108, v100
	v_mul_f32_e32 v125, v109, v101
	v_mul_f32_e32 v126, v110, v102
	v_mul_f32_e32 v127, v111, v103
	ds_write_b32 v76, v112
	ds_write_b32 v77, v113
	ds_write_b32 v78, v114
	ds_write_b32 v79, v115
	ds_write_b32 v76, v116 offset:64
	ds_write_b32 v77, v117 offset:64
	ds_write_b32 v78, v118 offset:64
	ds_write_b32 v79, v119 offset:64
	ds_write_b32 v76, v120 offset:128
	ds_write_b32 v77, v121 offset:128
	ds_write_b32 v78, v122 offset:128
	ds_write_b32 v79, v123 offset:128
	ds_write_b32 v76, v124 offset:192
	ds_write_b32 v77, v125 offset:192
	ds_write_b32 v78, v126 offset:192
	ds_write_b32 v79, v127 offset:192
	s_waitcnt lgkmcnt(15)
	v_mul_f32_e32 v208, v216, v188
	v_mul_f32_e32 v209, v217, v189
	v_mul_f32_e32 v210, v218, v190
	v_mul_f32_e32 v211, v219, v191
	v_mul_f32_e32 v212, v220, v192
	v_mul_f32_e32 v213, v221, v193
	v_mul_f32_e32 v214, v222, v194
	v_mul_f32_e32 v215, v223, v195
	v_mul_f32_e32 v200, v216, v180
	v_mul_f32_e32 v201, v217, v181
	v_mul_f32_e32 v202, v218, v182
	v_mul_f32_e32 v203, v219, v183
	v_mul_f32_e32 v204, v220, v184
	v_mul_f32_e32 v205, v221, v185
	v_mul_f32_e32 v206, v222, v186
	v_mul_f32_e32 v207, v223, v187
	ds_write_b128 v196, v[200:203]
	ds_write_b128 v196, v[204:207] offset:256
	ds_write_b128 v196, v[208:211] offset:512
	ds_write_b128 v196, v[212:215] offset:768
	ds_write_b32 v197, v111
	s_bfe_u32 s96, s62, 0x20006
	s_and_b32 s97, s96, 1
	s_mul_i32 s97, s97, 0x2700
	s_mov_b32 s101, 0x1c000
	s_mov_b32 s100, 0x6100
	s_bitcmp0_b32 s65, 0
	s_cselect_b32 s101, 0xe000, s101
	s_cselect_b32 s100, 0x4e00, s100
	s_cmp_gt_u32 s96, 1
	s_cselect_b32 s100, s100, 0
	s_add_i32 s97, s97, s101
	s_add_i32 s97, s97, s100
	s_mov_b32 s96, s97
	v_and_b32_e32 v72, 3, v233
	v_lshrrev_b32_e32 v73, 2, v233
	v_lshlrev_b32_e32 v72, 2, v72
	v_lshl_add_u32 v72, v73, 8, v72
	v_lshl_add_u32 v72, v234, 6, v72
	s_add_i32 s97, s96, 0x1000
	v_add_u32_e32 v78, s97, v72
	v_xor_b32_e32 v79, v224, v234
	v_lshl_add_u32 v79, v79, 4, s96
	ds_read_b128 v[96:99], v79
	ds_read_b128 v[100:103], v79 offset:1024
	ds_read_b128 v[104:107], v79 offset:2048
	ds_read_b128 v[108:111], v79 offset:3072
	ds_read_b32 v80, v78
	ds_read_b32 v81, v78 offset:16
	ds_read_b32 v82, v78 offset:32
	ds_read_b32 v83, v78 offset:48
	ds_read_b32 v84, v78 offset:1024
	ds_read_b32 v85, v78 offset:1040
	ds_read_b32 v86, v78 offset:1056
	ds_read_b32 v87, v78 offset:1072
	ds_read_b32 v88, v78 offset:2048
	ds_read_b32 v89, v78 offset:2064
	ds_read_b32 v90, v78 offset:2080
	ds_read_b32 v91, v78 offset:2096
	ds_read_b32 v92, v78 offset:3072
	ds_read_b32 v93, v78 offset:3088
	ds_read_b32 v94, v78 offset:3104
	ds_read_b32 v95, v78 offset:3120
	v_lshl_add_u32 v74, v224, 2, s96
	ds_write_b32 v74, v235 offset:9728
	v_add_u32_e32 v75, -1, v233
	v_mov_b32_e32 v76, -1
	v_cndmask_b32_e64 v75, v76, v75, s[98:99]
	v_cmp_lt_u32_e64 s[100:101], 7, v233
	v_add_u32_e32 v76, -8, v233
	v_and_b32_e32 v77, 1, v234
	v_cndmask_b32_e64 v75, v75, v76, s[100:101]
	v_lshlrev_b32_e32 v77, 2, v77
	v_sub_u32_e32 v76, v75, v77
	v_lshlrev_b32_e32 v77, 2, v234
	v_sub_u32_e32 v77, v233, v77
	v_add_u32_e32 v77, -1, v77
	s_waitcnt lgkmcnt(15)
	v_mfma_f32_16x16x4_f32 v[244:247], v80, v96, 0
	v_mfma_f32_16x16x4_f32 v[240:243], v81, v97, 0
	s_waitcnt lgkmcnt(14)
	v_mfma_f32_16x16x4_f32 v[244:247], v82, v98, v[244:247]
	s_waitcnt lgkmcnt(13)
	v_mfma_f32_16x16x4_f32 v[240:243], v83, v99, v[240:243]
	s_waitcnt lgkmcnt(12)
	v_mfma_f32_16x16x4_f32 v[244:247], v84, v100, v[244:247]
	s_waitcnt lgkmcnt(11)
	v_mfma_f32_16x16x4_f32 v[240:243], v85, v101, v[240:243]
	s_waitcnt lgkmcnt(10)
	v_mfma_f32_16x16x4_f32 v[244:247], v86, v102, v[244:247]
	s_waitcnt lgkmcnt(9)
	v_mfma_f32_16x16x4_f32 v[240:243], v87, v103, v[240:243]
	s_waitcnt lgkmcnt(8)
	v_mfma_f32_16x16x4_f32 v[244:247], v88, v104, v[244:247]
	s_waitcnt lgkmcnt(7)
	v_mfma_f32_16x16x4_f32 v[240:243], v89, v105, v[240:243]
	s_waitcnt lgkmcnt(6)
	v_mfma_f32_16x16x4_f32 v[244:247], v90, v106, v[244:247]
	s_waitcnt lgkmcnt(5)
	v_mfma_f32_16x16x4_f32 v[240:243], v91, v107, v[240:243]
	s_waitcnt lgkmcnt(4)
	v_mfma_f32_16x16x4_f32 v[244:247], v92, v108, v[244:247]
	s_waitcnt lgkmcnt(3)
	v_mfma_f32_16x16x4_f32 v[240:243], v93, v109, v[240:243]
	s_waitcnt lgkmcnt(2)
	v_mfma_f32_16x16x4_f32 v[244:247], v94, v110, v[244:247]
	s_waitcnt lgkmcnt(1)
	v_mfma_f32_16x16x4_f32 v[240:243], v95, v111, v[240:243]
	s_nop 9
	v_add_f32_e32 v244, v244, v240
	v_add_f32_e32 v245, v245, v241
	v_add_f32_e32 v246, v246, v242
	v_add_f32_e32 v247, v247, v243
	v_cmp_le_i32_e64 s[96:97], 0, v76
	v_cmp_le_i32_e64 s[100:101], 1, v76
	s_nop 0
	v_cndmask_b32_e64 v128, 0, v244, s[96:97]
	v_cndmask_b32_e64 v129, 0, v245, s[100:101]
	v_cmp_le_i32_e64 s[96:97], 2, v76
	v_cmp_le_i32_e64 s[100:101], 3, v76
	s_nop 0
	v_cndmask_b32_e64 v130, 0, v246, s[96:97]
	v_cndmask_b32_e64 v131, 0, v247, s[100:101]
	s_bfe_u32 s96, s62, 0x20006
	s_and_b32 s97, s96, 1
	s_mul_i32 s97, s97, 0x2700
	s_mov_b32 s101, 0x1c000
	s_mov_b32 s100, 0x6100
	s_bitcmp0_b32 s65, 0
	s_cselect_b32 s101, 0xe000, s101
	s_cselect_b32 s100, 0x4e00, s100
	s_cmp_gt_u32 s96, 1
	s_cselect_b32 s100, s100, 0
	s_add_i32 s97, s97, s101
	s_add_i32 s97, s97, s100
	v_xor_b32_e32 v74, v224, v234
	v_lshl_add_u32 v74, v74, 4, s97
	ds_write_b128 v74, v[128:131] offset:8448
	v_lshlrev_b32_e32 v75, 7, v234
	v_lshl_add_u32 v75, v233, 2, v75
	v_add_u32_e32 v75, s97, v75
	v_cmp_le_i32_e64 s[96:97], 0, v77
	v_cmp_le_i32_e64 s[100:101], 1, v77
	s_nop 0
	v_cndmask_b32_e64 v132, 0, v244, s[96:97]
	v_cndmask_b32_e64 v133, 0, v245, s[100:101]
	v_cmp_le_i32_e64 s[96:97], 2, v77
	v_cmp_le_i32_e64 s[100:101], 3, v77
	s_nop 0
	v_cndmask_b32_e64 v134, 0, v246, s[96:97]
	v_cndmask_b32_e64 v135, 0, v247, s[100:101]
	s_mov_b64 exec, 0x00ff00ff
	ds_write_b32 v75, v132 offset:9472
	ds_write_b32 v75, v133 offset:9504
	ds_write_b32 v75, v134 offset:9536
	ds_write_b32 v75, v135 offset:9568
	s_mov_b64 exec, -1
	s_setprio 0
	s_branch .LBB0_655
	s_nop 0
	s_nop 0
	s_nop 0
	s_nop 0
